# hc3q2
# baseline (speedup 1.0000x reference)
; __global__ void __launch_bounds__(512) fwd(Args a_) {
;     ...
;         } else if (PHM(3) && sp == 3) { PHASE_PROLOGUE
;             const unsigned* kmx = (const unsigned*)(a.ws + WS_CTL) + 8192 + 64 * (8 + 2 * L);
;             const float kb0 = 8.f * 1.01f * __uint_as_float(kmx[0]), kb1 = 8.f * 1.01f * __uint_as_float(kmx[64]);
;             const int gwx = ((G & 7) == 0 ? (bx & 7) * (G >> 3) + (bx >> 3) : bx) * 8 + wave;
;             for (int k = gwx; k < 2048; k += NGW) { nsa_item8(c, 2047 - (k >> 1), 1 - (k & 1), lds, wave, lane, (k & 1) ? kb0 : kb1); nsa_item8(c, k >> 1, k & 1, lds, wave, lane, (k & 1) ? kb1 : kb0); }
.LBB0_158:
	s_and_b64 vcc, exec, s[6:7]
	s_cbranch_vccz .LBB0_1228
	s_cmp_gt_i32 s44, 1
	s_mov_b64 s[6:7], -1
	s_cbranch_scc0 .LBB0_1173
	s_cmp_gt_i32 s44, 2
	v_writelane_b32 v244, s84, 28
	s_cbranch_scc0 .LBB0_1098
	v_readlane_b32 s101, v244, 7
	v_readlane_b32 s84, v244, 28
	s_nop 1
	s_bitcmp1_b32 s101, 0
	s_cbranch_scc0 .Lcq_p3_cont
	v_writelane_b32 v246, 2, 1
	s_lshl_b32 s100, s84, 1
	s_add_i32 s100, s100, 9
	s_branch .Lcq_entry
.Lcq_p3_cont:
	v_readlane_b32 s6, v244, 1
	v_readlane_b32 s7, v244, 2
	v_readlane_b32 s8, v244, 7
	v_readlane_b32 s9, v244, 0
	v_readlane_b32 s10, v244, 28
	s_load_dwordx2 s[6:7], s[6:7], 0xa0
	v_mbcnt_lo_u32_b32 v195, -1, 0
	v_mbcnt_hi_u32_b32 v195, -1, v195
	s_lshl_b32 s10, s10, 7
	s_addk_i32 s10, 0x200
	s_ashr_i32 s11, s10, 31
	s_lshl_b64 s[10:11], s[10:11], 2
	s_waitcnt lgkmcnt(0)
	s_add_u32 s10, s6, s10
	s_addc_u32 s11, s7, s11
	s_add_u32 s12, s10, 0x22208000
	s_addc_u32 s13, s11, 0
	global_load_dword v0, v231, s[10:11]
	global_load_dword v2, v1, s[12:13] offset:256
	v_readlane_b32 s10, v244, 11
	v_readlane_b32 s11, v244, 12
	s_andn2_b64 vcc, exec, s[10:11]
	s_cbranch_vccz .LBB0_163
	s_lshl_b32 s9, s9, 3
	s_add_i32 s73, s9, s8
	s_cmpk_gt_i32 s73, 0x7ff
	s_cbranch_scc0 .LBB0_164
	s_branch .LBB0_1097

; DI void conv_layer(const Ctx& c, const Args& a, int L, LAS unsigned char* lds, int gw, int NGW, int wave, int lane) {
;     LAS float* scr = (LAS float*)(lds + wave * 8704);
;     const float* Win = a.in[2] + (size_t)L * DM * 9752;
;     const float* Wg = a.in[15] + (size_t)L * DM * DFF; const float* Wu = a.in[16] + (size_t)L * DM * DFF; const float* Wd = a.in[17] + (size_t)L * DFF * DM;
;     ...
;     constexpr int NITEMS = (9984 / 32) * 32 + 3 * 64 * 8 + 64 * 32 + 2 * 176 * 32 + 64 * 88 + 2 * 8 * 32 + 2 * 2 * 4;
;     for (int it = gw; it < NITEMS; it += NGW) {
;         int rr = it;
;         SEG(Win, 9752, 2048, 3608, c.WinT, 3840, 192, 6144)
;         SEG(Win, 9752, 2048, 0, c.WinT, 0, 16, 512)
;         SEG(Win, 9752, 2048, 512, c.WinT, 2048, 4, 128)
;         SEG(Win, 9752, 2048, 640, c.WinT, 2816, 4, 128)
;         SEG(Win, 9752, 2048, 768, c.WinT, 512, 16, 512)
;         SEG(Win, 9752, 2048, 1280, c.WinT, 1024, 16, 512)
;         SEG(Win, 9752, 2048, 1792, c.WinT, 3328, 16, 512)
;         SEG(Win, 9752, 2048, 2304, c.WinT, 1536, 16, 512)
;         SEG(Win, 9752, 2048, 2816, c.WinT, 2176, 4, 128)
;         SEG(Win, 9752, 2048, 2944, c.WinT, 2304, 4, 128)
;         SEG(Win, 9752, 2048, 3072, c.WinT, 2432, 4, 128)
;         SEG(Win, 9752, 2048, 3200, c.WinT, 2944, 4, 128)
;         SEG(Win, 9752, 2048, 3328, c.WinT, 2560, 4, 128)
;         SEG(Win, 9752, 2048, 3456, c.WinT, 3072, 4, 128)
;         SEG(Win, 9752, 2048, 3584, c.WinT, 2688, 4, 24)
;         SEG(Win, 9752, 2048, 0, c.WinT, 3200, 4, 0)
;         SEG(a.in[10] + (size_t)L * 512 * DM, 2048, 512, 0, c.WbrT, 0, 64, 2048)
;         SEG(a.in[11] + (size_t)L * 512 * DM, 2048, 512, 0, c.WbrT + (size_t)2048 * 512, 0, 64, 2048)
;         SEG(a.in[12] + (size_t)L * 512 * DM, 2048, 512, 0, c.WbrT + (size_t)2 * 2048 * 512, 0, 64, 2048)
;         SEG(a.in[13] + (size_t)L * DM * DM, 2048, 2048, 0, c.WoutT, 0, 64, 2048)
;         { const int cnt = 176 * 32; if (rr < cnt) { const int kb = rr / 176, j = rr % 176; transpose_item(Wg, DFF, 2048, 64 * kb, 32 * j, 32, c.WguT, (j >> 2) * 256 + (j & 3) * 32, scr, lane); continue; } rr -= cnt; }
;         { const int cnt = 176 * 32; if (rr < cnt) { const int kb = rr / 176, j = rr % 176; transpose_item(Wu, DFF, 2048, 64 * kb, 32 * j, 32, c.WguT, (j >> 2) * 256 + 128 + (j & 3) * 32, scr, lane); continue; } rr -= cnt; }
;         SEG(Wd, 2048, 5632, 0, c.WdT, 0, 64, 2048)
.Lcq_entry:
	v_readlane_b32 s54, v244, 1
	v_readlane_b32 s55, v244, 2
	s_load_dwordx4 s[24:27], s[54:55], 0x0
	s_load_dwordx2 s[6:7], s[54:55], 0x10
	s_load_dwordx16 s[36:51], s[54:55], 0x20
	s_load_dwordx4 s[12:15], s[54:55], 0x98
	v_readlane_b32 s17, v244, 7
	v_readlane_b32 s34, v244, 0
	v_mbcnt_lo_u32_b32 v34, -1, 0
	v_mbcnt_hi_u32_b32 v34, -1, v34
	s_lshl_b32 s8, s34, 3
	s_mov_b32 s52, s84
	s_add_i32 s16, s8, s17
	s_ashr_i32 s53, s52, 31
	s_mov_b32 s31, s84
	s_cmpk_gt_i32 s16, 0x790f
	s_cbranch_scc1 .LBB0_1426
	s_load_dwordx4 s[8:11], s[54:55], 0x60
	s_load_dwordx4 s[84:87], s[54:55], 0x78
	s_nop 0
	s_load_dwordx2 s[54:55], s[54:55], 0x88
	s_mul_i32 s63, s52, 0x4c30000
	s_mul_hi_i32 s62, s52, 0x4c30000
	s_waitcnt lgkmcnt(0)
	s_add_u32 s6, s6, s63
	s_addc_u32 s7, s7, s62
	s_mul_i32 s62, s17, 0x2200
	s_add_i32 s72, s62, 0x10000
	s_cmp_eq_u32 s72, 0x1ee00
	s_cselect_b32 s72, 0x20100, s72
	s_mul_i32 s66, s52, 0x2c00000
	s_mul_hi_i32 s67, s52, 0x2c00000
	s_add_u32 s54, s54, s66
	s_addc_u32 s55, s55, s67
	s_waitcnt vmcnt(0)
	v_and_b32_e32 v2, 7, v34
	s_add_u32 s62, s86, s66
	v_ashrrev_i32_e32 v35, 3, v34
	v_lshlrev_b32_e32 v0, 4, v2
	s_movk_i32 s73, 0x84
	s_addc_u32 s63, s87, s67
	v_add_u32_e32 v37, s72, v0
	v_mul_lo_u32 v3, v35, s73
	s_add_u32 s66, s84, s66
	v_lshlrev_b32_e32 v36, 2, v2
	v_add_u32_e32 v86, v37, v3
	v_add_u32_e32 v88, 0x420, v3
	v_mul_u32_u24_e32 v2, 0x420, v2
	v_lshlrev_b32_e32 v3, 2, v35
	s_addc_u32 s67, s85, s67
	v_add3_u32 v91, s72, v2, v3
	s_lshl_b64 s[72:73], s[52:53], 22
	s_lshl_b64 s[84:85], s[52:53], 24
	v_lshl_add_u64 v[42:43], s[62:63], 0, v[0:1]
	v_lshl_add_u64 v[44:45], s[54:55], 0, v[0:1]
	s_lshl_b64 s[54:55], s[52:53], 21
	s_lshl_b64 s[62:63], s[52:53], 16
	s_add_u32 s48, s48, s72
	s_addc_u32 s49, s49, s73
	v_lshl_add_u64 v[68:69], s[48:49], 0, v[0:1]
	s_add_u32 s48, s50, s72
	s_addc_u32 s49, s51, s73
	s_add_u32 s8, s8, s72
	s_addc_u32 s9, s9, s73
	v_lshl_add_u64 v[40:41], s[66:67], 0, v[0:1]
	v_lshl_add_u64 v[46:47], s[14:15], 0, v[0:1]
	s_mov_b64 s[66:67], 0x2700000
	v_lshl_add_u64 v[72:73], s[8:9], 0, v[0:1]
	s_add_u32 s8, s10, s84
	v_lshl_add_u64 v[48:49], v[46:47], 0, s[66:67]
	s_mov_b64 s[66:67], 0x2d00000
	s_addc_u32 s9, s11, s85
	v_lshl_add_u64 v[50:51], v[46:47], 0, s[66:67]
	s_mov_b64 s[66:67], 0x3500000
	v_lshl_add_u64 v[74:75], s[8:9], 0, v[0:1]
	s_add_u32 s8, s38, s54
	v_lshl_add_u64 v[52:53], v[46:47], 0, s[66:67]
	s_mov_b64 s[66:67], 0x6100000
	s_addc_u32 s9, s39, s55
	v_lshl_add_u64 v[54:55], v[46:47], 0, s[66:67]
	s_mov_b64 s[66:67], 0x7700000
	v_lshl_add_u64 v[76:77], s[8:9], 0, v[0:1]
	s_add_u32 s8, s44, s54
	v_lshl_add_u64 v[56:57], v[46:47], 0, s[66:67]
	s_mov_b64 s[66:67], 0x7800000
	s_addc_u32 s9, s45, s55
	v_lshl_add_u64 v[58:59], v[46:47], 0, s[66:67]
	s_mov_b64 s[66:67], 0x7900000
	v_lshl_add_u64 v[78:79], s[8:9], 0, v[0:1]
	s_add_u32 s8, s40, s62
	v_lshl_add_u64 v[60:61], v[46:47], 0, s[66:67]
	s_mov_b64 s[66:67], 0x7908000
	s_addc_u32 s9, s41, s63
	v_lshl_add_u64 v[62:63], v[46:47], 0, s[66:67]
	s_mov_b64 s[66:67], 0x2900000
	v_lshl_add_u64 v[80:81], s[8:9], 0, v[0:1]
	s_add_u32 s8, s46, s62
	v_lshl_add_u64 v[64:65], v[46:47], 0, s[66:67]
	s_mov_b64 s[66:67], 0x2b00000
	s_addc_u32 s9, s47, s63
	v_add_u32_e32 v87, 8, v35
	v_add_u32_e32 v89, 16, v35
	v_add_u32_e32 v90, 24, v35
	v_lshl_add_u64 v[38:39], s[6:7], 0, v[0:1]
	v_lshl_add_u64 v[66:67], v[46:47], 0, s[66:67]
	v_lshl_add_u64 v[70:71], s[48:49], 0, v[0:1]
	v_lshl_add_u64 v[82:83], s[8:9], 0, v[0:1]
	s_cmp_eq_u32 s100, 0
	s_cbranch_scc0 .Lcq_job
	s_cmp_lg_u32 s52, 0
	s_cbranch_scc1 .Lcq_rms_fix
	s_mov_b32 s100, 5
	s_branch .Lcq_pb
.Lcq_job:
	s_cmp_eq_u32 s100, 5
	s_cbranch_scc1 .Lcq_pb
	s_cmp_eq_u32 s100, 6
	s_cbranch_scc1 .Lcq_pb
	s_branch .Lcq_pop
.LBB0_1262:
	s_add_i32 s101, s101, 8
	s_bfe_u32 vcc_lo, s101, 0x20003
	s_cmp_lg_u32 vcc_lo, 0
	s_cbranch_scc1 .Lcq_map
	s_bitcmp1_b32 s100, 3
	s_cbranch_scc0 .Lcq_pop
	v_readlane_b32 vcc_lo, v246, 1
	s_nop 1
	s_sub_u32 vcc_lo, vcc_lo, 1
	v_writelane_b32 v246, vcc_lo, 1
	s_cmp_eq_u32 vcc_lo, 0
	s_cbranch_scc1 .LBB0_1426
.Lcq_pop:
	s_and_b32 s101, s34, 7
	s_lshl_b32 s101, s101, 8
	s_and_b32 vcc_lo, s100, 7
	s_lshl_b32 vcc_lo, vcc_lo, 11
	s_add_i32 s101, s101, vcc_lo
	s_add_i32 s101, s101, 0x2220c000
	v_mov_b32_e32 v245, 1
	v_mov_b32_e32 v247, s101
	s_mov_b64 vcc, exec
	s_mov_b64 exec, 1
	global_atomic_add v246, v247, v245, s[14:15] sc0
	s_mov_b64 exec, vcc
	s_waitcnt vmcnt(0)
	v_readfirstlane_b32 s101, v246
	s_and_b32 vcc_lo, s34, 7
	s_nop 1
	s_lshl_b32 s101, s101, 5
	s_add_i32 s101, s101, vcc_lo

; __global__ void __launch_bounds__(512) fwd(Args a_) {
;     ...
;         } else if (PHM(3) && sp == 3) { PHASE_PROLOGUE
;             const unsigned* kmx = (const unsigned*)(a.ws + WS_CTL) + 8192 + 64 * (8 + 2 * L);
;             const float kb0 = 8.f * 1.01f * __uint_as_float(kmx[0]), kb1 = 8.f * 1.01f * __uint_as_float(kmx[64]);
;             const int gwx = ((G & 7) == 0 ? (bx & 7) * (G >> 3) + (bx >> 3) : bx) * 8 + wave;
;             for (int k = gwx; k < 2048; k += NGW) { nsa_item8(c, 2047 - (k >> 1), 1 - (k & 1), lds, wave, lane, (k & 1) ? kb0 : kb1); nsa_item8(c, k >> 1, k & 1, lds, wave, lane, (k & 1) ? kb1 : kb0); }
.Lcq_return:
	s_bitcmp1_b32 s100, 3
	s_cbranch_scc0 .Lcq_ret_tail
	s_mov_b32 s100, 0
	s_branch .Lcq_p3_cont
